# v27 plus SiLU gate epilogue: f32 rcp+mul instead of the 11-instruction IEEE divide sequence, dead chain code removed
# speedup vs baseline: 1.0032x; 1.0003x over previous
; DI void st4(u16* p, float a, float b, float c, float d) { u32x2 w = {cvtpk(a, b), cvtpk(c, d)}; *(u32x2*)p = w; }
;   DI void operator()(int m, int n, f32x4 v) const { st4(dst + (size_t)m * ld + n, v[0], v[1], v[2], v[3]); }
;   DI void operator()(int m, int n, f32x4 v) const {
;     float o[4];
; #pragma unroll
;     for (int q = 0; q < 4; ++q) o[q] = v[q] / (1.f + __expf(-v[q]));
;     st4(dst + (size_t)m * ld + n, o[0], o[1], o[2], o[3]);
;   }
.LBB0_218:
	s_lshl_b64 s[8:9], s[8:9], 20
	s_add_u32 s11, s12, s8
	s_addc_u32 s16, s13, s9
	s_lshl_b64 s[8:9], s[96:97], 1
	s_add_u32 s8, s11, s8
	s_movk_i32 s11, 0x2200
	v_cmp_gt_i32_e32 vcc, 3, v166
	v_mul_lo_u32 v128, v166, s11
	v_lshlrev_b32_e32 v132, 4, v164
	v_cndmask_b32_e32 v130, v143, v144, vcc
	v_add3_u32 v128, 16, v128, v130
	v_and_b32_e32 v130, 0x80, v132
	v_lshlrev_b32_e32 v131, 5, v165
	v_and_b32_e32 v133, 28, v168
	v_or3_b32 v137, v130, v131, v133
	v_lshlrev_b32_e32 v130, 2, v164
	v_mul_u32_u24_e32 v131, 0x440, v136
	v_add3_u32 v130, v128, v130, v131
	ds_write2_b32 v130, v104, v108 offset1:16
	ds_write2_b32 v130, v105, v109 offset0:68 offset1:84
	ds_write2_b32 v130, v106, v110 offset0:136 offset1:152
	ds_write2_b32 v130, v107, v111 offset0:204 offset1:220
	ds_write2_b32 v130, v120, v124 offset0:32 offset1:48
	ds_write2_b32 v130, v121, v125 offset0:100 offset1:116
	ds_write2_b32 v130, v122, v126 offset0:168 offset1:184
	ds_write2_b32 v130, v123, v127 offset0:236 offset1:252
	v_add_u32_e32 v127, 0x1000, v130
	v_add_u32_e32 v131, 0x1400, v130
	ds_write2_b32 v127, v96, v100 offset0:64 offset1:80
	ds_write2_b32 v127, v97, v101 offset0:132 offset1:148
	ds_write2_b32 v127, v98, v102 offset0:200 offset1:216
	ds_write2_b32 v131, v99, v103 offset0:12 offset1:28
	ds_write2_b32 v127, v112, v116 offset0:96 offset1:112
	ds_write2_b32 v127, v113, v117 offset0:164 offset1:180
	ds_write2_b32 v127, v114, v118 offset0:232 offset1:248
	ds_write2_b32 v131, v115, v119 offset0:44 offset1:60
	v_mul_u32_u24_e32 v96, 0x110, v136
	s_waitcnt lgkmcnt(0)
	v_add3_u32 v126, v128, v132, v96
	ds_read_b128 v[132:135], v126
	v_or_b32_e32 v124, v167, v136
	v_lshlrev_b32_e32 v128, 1, v137
	ds_read_b128 v[136:139], v126 offset:1088
	s_addc_u32 s9, s16, s9
	s_waitcnt lgkmcnt(0)
	v_mul_f32_e32 v98, 0xbfb8aa3b, v132
	v_exp_f32_e32 v98, v98
	v_lshl_add_u64 v[96:97], s[8:9], 0, v[128:129]
	s_mov_b64 s[8:9], 0x1f62a100
	v_lshl_add_u64 v[122:123], v[96:97], 0, s[8:9]
	v_add_f32_e32 v120, 1.0, v98
	v_mul_f32_e32 v141, 0xbfb8aa3b, v133
	v_exp_f32_e32 v141, v141
	ds_read_b128 v[116:119], v126 offset:2176
	ds_read_b128 v[112:115], v126 offset:3264
	v_add_f32_e32 v128, 1.0, v141
	v_mul_f32_e32 v125, 0xbfb8aa3b, v134
	v_exp_f32_e32 v125, v125
	v_rcp_f32_e32 v200, v120
	s_nop 0
	v_mul_f32_e32 v132, v132, v200
	v_add_f32_e32 v125, 1.0, v125
	v_rcp_f32_e32 v202, v128
	s_nop 0
	v_mul_f32_e32 v128, v133, v202
	v_mul_f32_e32 v133, 0xbfb8aa3b, v135
	v_exp_f32_e32 v133, v133
	s_nop 0
	v_add_f32_e32 v133, 1.0, v133
	v_div_scale_f32 v140, s[8:9], v133, v133, v135
	v_rcp_f32_e32 v146, v140
	v_rcp_f32_e32 v204, v125
	s_nop 0
	v_mul_f32_e32 v134, v134, v204
	ds_read_b128 v[108:111], v126 offset:4352
	ds_read_b128 v[104:107], v126 offset:5440
	ds_read_b128 v[100:103], v126 offset:6528
	ds_read_b128 v[96:99], v126 offset:7616
	v_fma_f32 v120, -v140, v146, 1.0
	v_fmac_f32_e32 v146, v120, v146
	v_rcp_f32_e32 v206, v133
	s_nop 0
	v_mul_f32_e32 v133, v135, v206
	v_mul_f32_e32 v120, 0xbfb8aa3b, v136
	v_exp_f32_e32 v135, v120
	v_ashrrev_i32_e32 v125, 31, v124
	v_lshlrev_b64 v[120:121], 12, v[124:125]
	v_cvt_pk_bf16_f32 v132, v132, v128
	v_add_f32_e32 v125, 1.0, v135
	v_lshl_add_u64 v[120:121], v[122:123], 0, v[120:121]
	v_cvt_pk_bf16_f32 v133, v134, v133
	global_store_dwordx2 v[120:121], v[132:133], off
	v_mul_f32_e32 v140, 0xbfb8aa3b, v137
	v_exp_f32_e32 v140, v140
	s_nop 0
	v_add_f32_e32 v133, 1.0, v140
	v_mul_f32_e32 v135, 0xbfb8aa3b, v138
	v_exp_f32_e32 v135, v135
	v_rcp_f32_e32 v200, v125
	s_nop 0
	v_mul_f32_e32 v125, v136, v200
	v_add_f32_e32 v135, 1.0, v135
	v_div_scale_f32 v136, s[8:9], v135, v135, v138
	v_rcp_f32_e32 v140, v136
	v_rcp_f32_e32 v202, v133
	s_nop 0
	v_mul_f32_e32 v128, v137, v202
	v_mul_f32_e32 v137, 0xbfb8aa3b, v139
	v_fma_f32 v133, -v136, v140, 1.0
	v_fmac_f32_e32 v140, v133, v140
	v_exp_f32_e32 v137, v137
	s_nop 0
	v_add_f32_e32 v136, 1.0, v137
	v_div_scale_f32 v137, s[8:9], v136, v136, v139
	v_rcp_f32_e32 v141, v137
	v_rcp_f32_e32 v204, v135
	s_nop 0
	v_mul_f32_e32 v135, v138, v204
	v_or_b32_e32 v132, 4, v124
	v_fma_f32 v133, -v137, v141, 1.0
	v_fmac_f32_e32 v141, v133, v141
	v_div_scale_f32 v133, vcc, v139, v136, v139
	v_mul_f32_e32 v134, v133, v141
	v_fma_f32 v138, -v137, v134, v133
	s_waitcnt lgkmcnt(0)
; DI void st4(u16* p, float a, float b, float c, float d) { u32x2 w = {cvtpk(a, b), cvtpk(c, d)}; *(u32x2*)p = w; }
;   DI void operator()(int m, int n, f32x4 v) const { st4(dst + (size_t)m * ld + n, v[0], v[1], v[2], v[3]); }
;   DI void operator()(int m, int n, f32x4 v) const {
;     float o[4];
; #pragma unroll
;     for (int q = 0; q < 4; ++q) o[q] = v[q] / (1.f + __expf(-v[q]));
;     st4(dst + (size_t)m * ld + n, o[0], o[1], o[2], o[3]);
;   }
	v_mul_f32_e32 v134, 0xbfb8aa3b, v116
	v_exp_f32_e32 v137, v134
	v_cvt_pk_bf16_f32 v134, v125, v128
	v_rcp_f32_e32 v206, v136
	s_nop 0
	v_mul_f32_e32 v136, v139, v206
	v_ashrrev_i32_e32 v133, 31, v132
	v_add_f32_e32 v125, 1.0, v137
	v_lshlrev_b64 v[132:133], 12, v[132:133]
	v_lshl_add_u64 v[132:133], v[122:123], 0, v[132:133]
	v_cvt_pk_bf16_f32 v135, v135, v136
	global_store_dwordx2 v[132:133], v[134:135], off
	v_mul_f32_e32 v135, 0xbfb8aa3b, v117
	v_exp_f32_e32 v135, v135
	s_nop 0
	v_add_f32_e32 v133, 1.0, v135
	v_mul_f32_e32 v134, 0xbfb8aa3b, v118
	v_rcp_f32_e32 v200, v125
	s_nop 0
	v_mul_f32_e32 v125, v116, v200
	v_exp_f32_e32 v134, v134
	s_nop 0
	v_add_f32_e32 v134, 1.0, v134
	v_div_scale_f32 v135, s[8:9], v134, v134, v118
	v_rcp_f32_e32 v137, v135
	v_rcp_f32_e32 v202, v133
	s_nop 0
	v_mul_f32_e32 v128, v117, v202
	v_mul_f32_e32 v133, 0xbfb8aa3b, v119
	v_fma_f32 v116, -v135, v137, 1.0
	v_exp_f32_e32 v133, v133
	v_fmac_f32_e32 v137, v116, v137
	v_add_f32_e32 v133, 1.0, v133
	v_div_scale_f32 v135, s[8:9], v133, v133, v119
	v_rcp_f32_e32 v136, v135
	v_rcp_f32_e32 v204, v134
	s_nop 0
	v_mul_f32_e32 v134, v118, v204
	v_or_b32_e32 v132, 8, v124
	v_fma_f32 v116, -v135, v136, 1.0
	v_fmac_f32_e32 v136, v116, v136
	v_rcp_f32_e32 v206, v133
	s_nop 0
	v_mul_f32_e32 v119, v119, v206
	v_mul_f32_e32 v116, 0xbfb8aa3b, v112
	v_exp_f32_e32 v135, v116
	v_cvt_pk_bf16_f32 v118, v125, v128
	v_ashrrev_i32_e32 v133, 31, v132
	v_lshlrev_b64 v[116:117], 12, v[132:133]
	v_add_f32_e32 v125, 1.0, v135
	v_lshl_add_u64 v[116:117], v[122:123], 0, v[116:117]
	v_cvt_pk_bf16_f32 v119, v134, v119
	global_store_dwordx2 v[116:117], v[118:119], off
	v_mul_f32_e32 v119, 0xbfb8aa3b, v113
	v_exp_f32_e32 v119, v119
	s_nop 0
	v_add_f32_e32 v119, 1.0, v119
	v_rcp_f32_e32 v200, v125
	s_nop 0
	v_mul_f32_e32 v118, v112, v200
	v_mul_f32_e32 v125, 0xbfb8aa3b, v114
	v_exp_f32_e32 v125, v125
	s_nop 0
	v_add_f32_e32 v125, 1.0, v125
	v_div_scale_f32 v128, s[8:9], v125, v125, v114
	v_rcp_f32_e32 v132, v128
	v_mul_f32_e32 v117, 0xbfb8aa3b, v115
	v_rcp_f32_e32 v202, v119
	s_nop 0
	v_mul_f32_e32 v119, v113, v202
	v_fma_f32 v112, -v128, v132, 1.0
	v_exp_f32_e32 v117, v117
	v_fmac_f32_e32 v132, v112, v132
	v_add_f32_e32 v117, 1.0, v117
	v_div_scale_f32 v128, s[8:9], v117, v117, v115
	v_rcp_f32_e32 v133, v128
	v_rcp_f32_e32 v204, v125
	s_nop 0
	v_mul_f32_e32 v125, v114, v204
	v_or_b32_e32 v116, 12, v124
	v_fma_f32 v112, -v128, v133, 1.0
	v_fmac_f32_e32 v133, v112, v133
	v_rcp_f32_e32 v206, v117
	s_nop 0
	v_mul_f32_e32 v115, v115, v206
	v_mul_f32_e32 v112, 0xbfb8aa3b, v108
	v_exp_f32_e32 v128, v112
	v_ashrrev_i32_e32 v117, 31, v116
	v_lshlrev_b64 v[112:113], 12, v[116:117]
	v_cvt_pk_bf16_f32 v114, v118, v119
	v_add_f32_e32 v116, 1.0, v128
	v_lshl_add_u64 v[112:113], v[122:123], 0, v[112:113]
	v_cvt_pk_bf16_f32 v115, v125, v115
	global_store_dwordx2 v[112:113], v[114:115], off
	v_mul_f32_e32 v115, 0xbfb8aa3b, v109
	v_exp_f32_e32 v115, v115
	s_nop 0
	v_add_f32_e32 v115, 1.0, v115
	v_rcp_f32_e32 v200, v116
	s_nop 0
	v_mul_f32_e32 v114, v108, v200
	v_mul_f32_e32 v116, 0xbfb8aa3b, v110
	v_exp_f32_e32 v116, v116
	s_nop 0
	v_add_f32_e32 v116, 1.0, v116
	v_div_scale_f32 v117, s[8:9], v116, v116, v110
	v_rcp_f32_e32 v118, v117
	v_mul_f32_e32 v113, 0xbfb8aa3b, v111
	v_rcp_f32_e32 v202, v115
	s_nop 0
	v_mul_f32_e32 v115, v109, v202
	v_fma_f32 v108, -v117, v118, 1.0
	v_exp_f32_e32 v113, v113
	v_fmac_f32_e32 v118, v108, v118
	v_add_f32_e32 v113, 1.0, v113
	v_div_scale_f32 v117, s[8:9], v113, v113, v111
	v_rcp_f32_e32 v119, v117
	v_rcp_f32_e32 v204, v116
	s_nop 0
	v_mul_f32_e32 v116, v110, v204
	v_or_b32_e32 v112, 16, v124
	v_fma_f32 v108, -v117, v119, 1.0
	v_fmac_f32_e32 v119, v108, v119
	v_rcp_f32_e32 v206, v113
	s_nop 0
	v_mul_f32_e32 v111, v111, v206
	v_mul_f32_e32 v108, 0xbfb8aa3b, v104
	v_exp_f32_e32 v117, v108
	v_ashrrev_i32_e32 v113, 31, v112
	v_lshlrev_b64 v[108:109], 12, v[112:113]
	v_cvt_pk_bf16_f32 v110, v114, v115
	v_add_f32_e32 v112, 1.0, v117
	v_lshl_add_u64 v[108:109], v[122:123], 0, v[108:109]
	v_cvt_pk_bf16_f32 v111, v116, v111
	global_store_dwordx2 v[108:109], v[110:111], off
	v_mul_f32_e32 v111, 0xbfb8aa3b, v105
	v_exp_f32_e32 v111, v111
	s_nop 0
	v_add_f32_e32 v111, 1.0, v111
	v_rcp_f32_e32 v200, v112
	s_nop 0
	v_mul_f32_e32 v110, v104, v200
	v_mul_f32_e32 v112, 0xbfb8aa3b, v106
	v_exp_f32_e32 v112, v112
	s_nop 0
	v_add_f32_e32 v112, 1.0, v112
	v_div_scale_f32 v113, s[8:9], v112, v112, v106
	v_rcp_f32_e32 v114, v113
	v_mul_f32_e32 v109, 0xbfb8aa3b, v107
	v_rcp_f32_e32 v202, v111
	s_nop 0
	v_mul_f32_e32 v111, v105, v202
	v_fma_f32 v104, -v113, v114, 1.0
	v_exp_f32_e32 v109, v109
	v_fmac_f32_e32 v114, v104, v114
	v_add_f32_e32 v109, 1.0, v109
	v_div_scale_f32 v113, s[8:9], v109, v109, v107
	v_rcp_f32_e32 v115, v113
	v_rcp_f32_e32 v204, v112
	s_nop 0
	v_mul_f32_e32 v112, v106, v204
	v_or_b32_e32 v108, 20, v124
	v_fma_f32 v104, -v113, v115, 1.0
	v_fmac_f32_e32 v115, v104, v115
	v_rcp_f32_e32 v206, v109
	s_nop 0
	v_mul_f32_e32 v107, v107, v206
	v_mul_f32_e32 v104, 0xbfb8aa3b, v100
	v_exp_f32_e32 v113, v104
	v_ashrrev_i32_e32 v109, 31, v108
	v_lshlrev_b64 v[104:105], 12, v[108:109]
	v_cvt_pk_bf16_f32 v106, v110, v111
	v_add_f32_e32 v108, 1.0, v113
	v_lshl_add_u64 v[104:105], v[122:123], 0, v[104:105]
	v_cvt_pk_bf16_f32 v107, v112, v107
	global_store_dwordx2 v[104:105], v[106:107], off
	v_mul_f32_e32 v107, 0xbfb8aa3b, v101
	v_exp_f32_e32 v107, v107
	s_nop 0
	v_add_f32_e32 v107, 1.0, v107
	v_rcp_f32_e32 v200, v108
	s_nop 0
	v_mul_f32_e32 v106, v100, v200
	v_mul_f32_e32 v108, 0xbfb8aa3b, v102
	v_exp_f32_e32 v108, v108
	s_nop 0
	v_add_f32_e32 v108, 1.0, v108
	v_div_scale_f32 v109, s[8:9], v108, v108, v102
; DI void st4(u16* p, float a, float b, float c, float d) { u32x2 w = {cvtpk(a, b), cvtpk(c, d)}; *(u32x2*)p = w; }
;   DI void operator()(int m, int n, f32x4 v) const { st4(dst + (size_t)m * ld + n, v[0], v[1], v[2], v[3]); }
;   DI void operator()(int m, int n, f32x4 v) const {
;     float o[4];
; #pragma unroll
;     for (int q = 0; q < 4; ++q) o[q] = v[q] / (1.f + __expf(-v[q]));
;     st4(dst + (size_t)m * ld + n, o[0], o[1], o[2], o[3]);
;   }
	v_rcp_f32_e32 v110, v109
	v_mul_f32_e32 v105, 0xbfb8aa3b, v103
	v_rcp_f32_e32 v202, v107
	s_nop 0
	v_mul_f32_e32 v107, v101, v202
	v_fma_f32 v100, -v109, v110, 1.0
	v_exp_f32_e32 v105, v105
	v_fmac_f32_e32 v110, v100, v110
	v_add_f32_e32 v105, 1.0, v105
	v_div_scale_f32 v109, s[8:9], v105, v105, v103
	v_rcp_f32_e32 v111, v109
	v_rcp_f32_e32 v204, v108
	s_nop 0
	v_mul_f32_e32 v108, v102, v204
	v_or_b32_e32 v104, 24, v124
	v_fma_f32 v100, -v109, v111, 1.0
	v_fmac_f32_e32 v111, v100, v111
	v_rcp_f32_e32 v206, v105
	s_nop 0
	v_mul_f32_e32 v103, v103, v206
	v_mul_f32_e32 v100, 0xbfb8aa3b, v96
	v_exp_f32_e32 v109, v100
	v_ashrrev_i32_e32 v105, 31, v104
	v_lshlrev_b64 v[100:101], 12, v[104:105]
	v_cvt_pk_bf16_f32 v102, v106, v107
	v_add_f32_e32 v104, 1.0, v109
	v_lshl_add_u64 v[100:101], v[122:123], 0, v[100:101]
	v_cvt_pk_bf16_f32 v103, v108, v103
	global_store_dwordx2 v[100:101], v[102:103], off
	v_mul_f32_e32 v103, 0xbfb8aa3b, v97
	v_exp_f32_e32 v103, v103
	s_nop 0
	v_add_f32_e32 v103, 1.0, v103
	v_rcp_f32_e32 v200, v104
	s_nop 0
	v_mul_f32_e32 v102, v96, v200
	v_mul_f32_e32 v104, 0xbfb8aa3b, v98
	v_exp_f32_e32 v104, v104
	s_nop 0
	v_add_f32_e32 v104, 1.0, v104
	v_div_scale_f32 v105, s[8:9], v104, v104, v98
	v_rcp_f32_e32 v106, v105
	v_mul_f32_e32 v101, 0xbfb8aa3b, v99
	v_rcp_f32_e32 v202, v103
	s_nop 0
	v_mul_f32_e32 v103, v97, v202
	v_fma_f32 v96, -v105, v106, 1.0
	v_exp_f32_e32 v101, v101
	v_fmac_f32_e32 v106, v96, v106
	v_add_f32_e32 v101, 1.0, v101
	v_div_scale_f32 v105, s[8:9], v101, v101, v99
	v_rcp_f32_e32 v107, v105
	v_rcp_f32_e32 v204, v104
	s_nop 0
	v_mul_f32_e32 v104, v98, v204
	v_or_b32_e32 v100, 28, v124
	v_fma_f32 v96, -v105, v107, 1.0
	v_fmac_f32_e32 v107, v96, v107
	v_rcp_f32_e32 v206, v101
	s_nop 0
	v_mul_f32_e32 v99, v99, v206
	v_ashrrev_i32_e32 v101, 31, v100
	v_lshlrev_b64 v[96:97], 12, v[100:101]
	v_lshl_add_u64 v[96:97], v[122:123], 0, v[96:97]
	v_cvt_pk_bf16_f32 v98, v102, v103
	v_cvt_pk_bf16_f32 v99, v104, v99
	global_store_dwordx2 v[96:97], v[98:99], off
	s_waitcnt lgkmcnt(0)
	ds_write2_b32 v130, v72, v76 offset1:16
	ds_write2_b32 v130, v73, v77 offset0:68 offset1:84
	ds_write2_b32 v130, v74, v78 offset0:136 offset1:152
	ds_write2_b32 v130, v75, v79 offset0:204 offset1:220
	ds_write2_b32 v130, v88, v92 offset0:32 offset1:48
	ds_write2_b32 v130, v89, v93 offset0:100 offset1:116
	ds_write2_b32 v130, v90, v94 offset0:168 offset1:184
	ds_write2_b32 v130, v91, v95 offset0:236 offset1:252
	ds_write2_b32 v127, v64, v68 offset0:64 offset1:80
	ds_write2_b32 v127, v65, v69 offset0:132 offset1:148
	ds_write2_b32 v127, v66, v70 offset0:200 offset1:216
	ds_write2_b32 v131, v67, v71 offset0:12 offset1:28
	ds_write2_b32 v127, v80, v84 offset0:96 offset1:112
	ds_write2_b32 v127, v81, v85 offset0:164 offset1:180
	ds_write2_b32 v127, v82, v86 offset0:232 offset1:248
	ds_write2_b32 v131, v83, v87 offset0:44 offset1:60
	s_waitcnt lgkmcnt(0)
	ds_read_b128 v[88:91], v126
	ds_read_b128 v[92:95], v126 offset:1088
	v_or_b32_e32 v96, 32, v124
	ds_read_b128 v[84:87], v126 offset:2176
	ds_read_b128 v[80:83], v126 offset:3264
	ds_read_b128 v[76:79], v126 offset:4352
	ds_read_b128 v[72:75], v126 offset:5440
	s_mov_b64 s[76:77], 0
	s_waitcnt lgkmcnt(0)
	v_mul_f32_e32 v64, 0xbfb8aa3b, v88
	v_exp_f32_e32 v64, v64
	v_mul_f32_e32 v102, 0xbfb8aa3b, v89
	v_exp_f32_e32 v102, v102
	v_add_f32_e32 v97, 1.0, v64
	ds_read_b128 v[68:71], v126 offset:6528
	ds_read_b128 v[64:67], v126 offset:7616
	v_add_f32_e32 v100, 1.0, v102
	v_mul_f32_e32 v99, 0xbfb8aa3b, v90
	v_exp_f32_e32 v99, v99
	v_rcp_f32_e32 v200, v97
	s_nop 0
	v_mul_f32_e32 v98, v88, v200
	v_add_f32_e32 v99, 1.0, v99
	v_div_scale_f32 v101, s[8:9], v99, v99, v90
	v_rcp_f32_e32 v102, v101
	v_mul_f32_e32 v97, 0xbfb8aa3b, v91
	v_rcp_f32_e32 v202, v100
	s_nop 0
	v_mul_f32_e32 v100, v89, v202
	v_fma_f32 v88, -v101, v102, 1.0
	v_exp_f32_e32 v97, v97
	v_fmac_f32_e32 v102, v88, v102
	v_add_f32_e32 v97, 1.0, v97
	v_div_scale_f32 v101, s[8:9], v97, v97, v91
	v_rcp_f32_e32 v103, v101
	v_rcp_f32_e32 v204, v99
	s_nop 0
	v_mul_f32_e32 v99, v90, v204
	v_fma_f32 v88, -v101, v103, 1.0
	v_fmac_f32_e32 v103, v88, v103
	v_rcp_f32_e32 v206, v97
	s_nop 0
	v_mul_f32_e32 v91, v91, v206
	v_mul_f32_e32 v88, 0xbfb8aa3b, v92
	v_exp_f32_e32 v101, v88
	v_ashrrev_i32_e32 v97, 31, v96
	v_lshlrev_b64 v[88:89], 12, v[96:97]
	v_cvt_pk_bf16_f32 v90, v98, v100
	v_add_f32_e32 v96, 1.0, v101
	v_lshl_add_u64 v[88:89], v[122:123], 0, v[88:89]
	v_cvt_pk_bf16_f32 v91, v99, v91
	global_store_dwordx2 v[88:89], v[90:91], off
	v_mul_f32_e32 v91, 0xbfb8aa3b, v93
	v_exp_f32_e32 v91, v91
	s_nop 0
	v_add_f32_e32 v91, 1.0, v91
	v_rcp_f32_e32 v200, v96
	s_nop 0
	v_mul_f32_e32 v90, v92, v200
	v_mul_f32_e32 v96, 0xbfb8aa3b, v94
	v_exp_f32_e32 v96, v96
	s_nop 0
	v_add_f32_e32 v96, 1.0, v96
	v_div_scale_f32 v97, s[8:9], v96, v96, v94
	v_rcp_f32_e32 v98, v97
	v_rcp_f32_e32 v202, v91
	s_nop 0
	v_mul_f32_e32 v91, v93, v202
	v_mul_f32_e32 v93, 0xbfb8aa3b, v95
	v_fma_f32 v89, -v97, v98, 1.0
	v_exp_f32_e32 v93, v93
	v_fmac_f32_e32 v98, v89, v98
	v_add_f32_e32 v93, 1.0, v93
	v_div_scale_f32 v97, s[8:9], v93, v93, v95
	v_rcp_f32_e32 v99, v97
	v_rcp_f32_e32 v204, v96
	s_nop 0
	v_mul_f32_e32 v92, v94, v204
	v_or_b32_e32 v88, 36, v124
	v_fma_f32 v89, -v97, v99, 1.0
	v_fmac_f32_e32 v99, v89, v99
	v_mul_f32_e32 v94, 0xbfb8aa3b, v84
	v_exp_f32_e32 v94, v94
	v_rcp_f32_e32 v206, v93
	s_nop 0
	v_mul_f32_e32 v93, v95, v206
	v_ashrrev_i32_e32 v89, 31, v88
	v_lshlrev_b64 v[88:89], 12, v[88:89]
	v_add_f32_e32 v94, 1.0, v94
	v_div_scale_f32 v95, s[8:9], v94, v94, v84
	v_rcp_f32_e32 v96, v95
	v_lshl_add_u64 v[88:89], v[122:123], 0, v[88:89]
	v_cvt_pk_bf16_f32 v90, v90, v91
; DI void st4(u16* p, float a, float b, float c, float d) { u32x2 w = {cvtpk(a, b), cvtpk(c, d)}; *(u32x2*)p = w; }
;   DI void operator()(int m, int n, f32x4 v) const { st4(dst + (size_t)m * ld + n, v[0], v[1], v[2], v[3]); }
;   DI void operator()(int m, int n, f32x4 v) const {
;     float o[4];
; #pragma unroll
;     for (int q = 0; q < 4; ++q) o[q] = v[q] / (1.f + __expf(-v[q]));
;     st4(dst + (size_t)m * ld + n, o[0], o[1], o[2], o[3]);
	v_cvt_pk_bf16_f32 v91, v92, v93
	global_store_dwordx2 v[88:89], v[90:91], off
	v_mul_f32_e32 v91, 0xbfb8aa3b, v85
	v_exp_f32_e32 v91, v91
	v_fma_f32 v89, -v95, v96, 1.0
	v_fmac_f32_e32 v96, v89, v96
	v_add_f32_e32 v91, 1.0, v91
	v_rcp_f32_e32 v200, v94
	s_nop 0
	v_mul_f32_e32 v90, v84, v200
	v_mul_f32_e32 v94, 0xbfb8aa3b, v86
	v_exp_f32_e32 v94, v94
	s_nop 0
	v_add_f32_e32 v92, 1.0, v94
	v_div_scale_f32 v94, s[8:9], v92, v92, v86
	v_rcp_f32_e32 v95, v94
	v_mul_f32_e32 v89, 0xbfb8aa3b, v87
	v_exp_f32_e32 v89, v89
	v_rcp_f32_e32 v202, v91
	s_nop 0
	v_mul_f32_e32 v91, v85, v202
	v_fma_f32 v84, -v94, v95, 1.0
	v_fmac_f32_e32 v95, v84, v95
	v_add_f32_e32 v89, 1.0, v89
	v_div_scale_f32 v93, s[8:9], v89, v89, v87
	v_rcp_f32_e32 v94, v93
	v_rcp_f32_e32 v204, v92
	s_nop 0
	v_mul_f32_e32 v92, v86, v204
	v_or_b32_e32 v88, 40, v124
	v_fma_f32 v84, -v93, v94, 1.0
	v_fmac_f32_e32 v94, v84, v94
	v_rcp_f32_e32 v206, v89
	s_nop 0
	v_mul_f32_e32 v87, v87, v206
	v_mul_f32_e32 v84, 0xbfb8aa3b, v80
	v_exp_f32_e32 v93, v84
	v_ashrrev_i32_e32 v89, 31, v88
	v_lshlrev_b64 v[84:85], 12, v[88:89]
	v_cvt_pk_bf16_f32 v86, v90, v91
	v_add_f32_e32 v88, 1.0, v93
	v_lshl_add_u64 v[84:85], v[122:123], 0, v[84:85]
	v_cvt_pk_bf16_f32 v87, v92, v87
	global_store_dwordx2 v[84:85], v[86:87], off
	v_mul_f32_e32 v87, 0xbfb8aa3b, v81
	v_exp_f32_e32 v87, v87
	s_nop 0
	v_add_f32_e32 v87, 1.0, v87
	v_rcp_f32_e32 v200, v88
	s_nop 0
	v_mul_f32_e32 v86, v80, v200
	v_mul_f32_e32 v88, 0xbfb8aa3b, v82
	v_exp_f32_e32 v88, v88
	s_nop 0
	v_add_f32_e32 v88, 1.0, v88
	v_div_scale_f32 v89, s[8:9], v88, v88, v82
	v_rcp_f32_e32 v90, v89
	v_mul_f32_e32 v85, 0xbfb8aa3b, v83
	v_rcp_f32_e32 v202, v87
	s_nop 0
	v_mul_f32_e32 v87, v81, v202
	v_fma_f32 v80, -v89, v90, 1.0
	v_exp_f32_e32 v85, v85
	v_fmac_f32_e32 v90, v80, v90
	v_add_f32_e32 v85, 1.0, v85
	v_div_scale_f32 v89, s[8:9], v85, v85, v83
	v_rcp_f32_e32 v91, v89
	v_rcp_f32_e32 v204, v88
	s_nop 0
	v_mul_f32_e32 v88, v82, v204
	v_or_b32_e32 v84, 44, v124
	v_fma_f32 v80, -v89, v91, 1.0
	v_fmac_f32_e32 v91, v80, v91
	v_rcp_f32_e32 v206, v85
	s_nop 0
	v_mul_f32_e32 v83, v83, v206
	v_mul_f32_e32 v80, 0xbfb8aa3b, v76
	v_exp_f32_e32 v89, v80
	v_ashrrev_i32_e32 v85, 31, v84
	v_lshlrev_b64 v[80:81], 12, v[84:85]
	v_cvt_pk_bf16_f32 v82, v86, v87
	v_add_f32_e32 v84, 1.0, v89
	v_lshl_add_u64 v[80:81], v[122:123], 0, v[80:81]
	v_cvt_pk_bf16_f32 v83, v88, v83
	global_store_dwordx2 v[80:81], v[82:83], off
	v_mul_f32_e32 v83, 0xbfb8aa3b, v77
	v_exp_f32_e32 v83, v83
	s_nop 0
	v_add_f32_e32 v83, 1.0, v83
	v_rcp_f32_e32 v200, v84
	s_nop 0
	v_mul_f32_e32 v82, v76, v200
	v_mul_f32_e32 v84, 0xbfb8aa3b, v78
	v_exp_f32_e32 v84, v84
	s_nop 0
	v_add_f32_e32 v84, 1.0, v84
	v_div_scale_f32 v85, s[8:9], v84, v84, v78
	v_rcp_f32_e32 v86, v85
	v_mul_f32_e32 v81, 0xbfb8aa3b, v79
	v_rcp_f32_e32 v202, v83
	s_nop 0
	v_mul_f32_e32 v83, v77, v202
	v_fma_f32 v76, -v85, v86, 1.0
	v_exp_f32_e32 v81, v81
	v_fmac_f32_e32 v86, v76, v86
	v_add_f32_e32 v81, 1.0, v81
	v_div_scale_f32 v85, s[8:9], v81, v81, v79
	v_rcp_f32_e32 v87, v85
	v_rcp_f32_e32 v204, v84
	s_nop 0
	v_mul_f32_e32 v84, v78, v204
	v_or_b32_e32 v80, 48, v124
	v_fma_f32 v76, -v85, v87, 1.0
	v_fmac_f32_e32 v87, v76, v87
	v_rcp_f32_e32 v206, v81
	s_nop 0
	v_mul_f32_e32 v79, v79, v206
	v_mul_f32_e32 v76, 0xbfb8aa3b, v72
	v_exp_f32_e32 v85, v76
	v_ashrrev_i32_e32 v81, 31, v80
	v_lshlrev_b64 v[76:77], 12, v[80:81]
	v_cvt_pk_bf16_f32 v78, v82, v83
	v_add_f32_e32 v80, 1.0, v85
	v_lshl_add_u64 v[76:77], v[122:123], 0, v[76:77]
	v_cvt_pk_bf16_f32 v79, v84, v79
	global_store_dwordx2 v[76:77], v[78:79], off
	v_mul_f32_e32 v79, 0xbfb8aa3b, v73
	v_exp_f32_e32 v79, v79
	s_nop 0
	v_add_f32_e32 v79, 1.0, v79
	v_rcp_f32_e32 v200, v80
	s_nop 0
	v_mul_f32_e32 v78, v72, v200
	v_mul_f32_e32 v80, 0xbfb8aa3b, v74
	v_exp_f32_e32 v80, v80
	s_nop 0
	v_add_f32_e32 v80, 1.0, v80
	v_div_scale_f32 v81, s[8:9], v80, v80, v74
	v_rcp_f32_e32 v82, v81
	v_mul_f32_e32 v77, 0xbfb8aa3b, v75
	v_rcp_f32_e32 v202, v79
	s_nop 0
	v_mul_f32_e32 v79, v73, v202
	v_fma_f32 v72, -v81, v82, 1.0
	v_exp_f32_e32 v77, v77
	v_fmac_f32_e32 v82, v72, v82
	v_add_f32_e32 v77, 1.0, v77
	v_div_scale_f32 v81, s[8:9], v77, v77, v75
	v_rcp_f32_e32 v83, v81
	v_rcp_f32_e32 v204, v80
	s_nop 0
	v_mul_f32_e32 v80, v74, v204
	v_or_b32_e32 v76, 52, v124
	v_fma_f32 v72, -v81, v83, 1.0
	v_fmac_f32_e32 v83, v72, v83
	v_rcp_f32_e32 v206, v77
	s_nop 0
	v_mul_f32_e32 v75, v75, v206
	s_waitcnt lgkmcnt(0)
; DI void st4(u16* p, float a, float b, float c, float d) { u32x2 w = {cvtpk(a, b), cvtpk(c, d)}; *(u32x2*)p = w; }
;   DI void operator()(int m, int n, f32x4 v) const { st4(dst + (size_t)m * ld + n, v[0], v[1], v[2], v[3]); }
;   DI void operator()(int m, int n, f32x4 v) const {
;     float o[4];
; #pragma unroll
;     for (int q = 0; q < 4; ++q) o[q] = v[q] / (1.f + __expf(-v[q]));
;     st4(dst + (size_t)m * ld + n, o[0], o[1], o[2], o[3]);
	v_mul_f32_e32 v72, 0xbfb8aa3b, v68
	v_exp_f32_e32 v81, v72
	v_ashrrev_i32_e32 v77, 31, v76
	v_lshlrev_b64 v[72:73], 12, v[76:77]
	v_cvt_pk_bf16_f32 v74, v78, v79
	v_add_f32_e32 v76, 1.0, v81
	v_lshl_add_u64 v[72:73], v[122:123], 0, v[72:73]
	v_cvt_pk_bf16_f32 v75, v80, v75
	global_store_dwordx2 v[72:73], v[74:75], off
	v_mul_f32_e32 v75, 0xbfb8aa3b, v69
	v_exp_f32_e32 v75, v75
	s_nop 0
	v_add_f32_e32 v75, 1.0, v75
	v_rcp_f32_e32 v200, v76
	s_nop 0
	v_mul_f32_e32 v74, v68, v200
	v_mul_f32_e32 v76, 0xbfb8aa3b, v70
	v_exp_f32_e32 v76, v76
	s_nop 0
	v_add_f32_e32 v76, 1.0, v76
	v_div_scale_f32 v77, s[8:9], v76, v76, v70
	v_rcp_f32_e32 v78, v77
	v_mul_f32_e32 v73, 0xbfb8aa3b, v71
	v_rcp_f32_e32 v202, v75
	s_nop 0
	v_mul_f32_e32 v75, v69, v202
	v_fma_f32 v68, -v77, v78, 1.0
	v_exp_f32_e32 v73, v73
	v_fmac_f32_e32 v78, v68, v78
	v_add_f32_e32 v73, 1.0, v73
	v_div_scale_f32 v77, s[8:9], v73, v73, v71
	v_rcp_f32_e32 v79, v77
	v_rcp_f32_e32 v204, v76
	s_nop 0
	v_mul_f32_e32 v76, v70, v204
	v_or_b32_e32 v72, 56, v124
	v_fma_f32 v68, -v77, v79, 1.0
	v_fmac_f32_e32 v79, v68, v79
	v_rcp_f32_e32 v206, v73
	s_nop 0
	v_mul_f32_e32 v71, v71, v206
	v_mul_f32_e32 v68, 0xbfb8aa3b, v64
	v_exp_f32_e32 v77, v68
	v_ashrrev_i32_e32 v73, 31, v72
	v_lshlrev_b64 v[68:69], 12, v[72:73]
	v_cvt_pk_bf16_f32 v70, v74, v75
	v_add_f32_e32 v72, 1.0, v77
	v_lshl_add_u64 v[68:69], v[122:123], 0, v[68:69]
	v_cvt_pk_bf16_f32 v71, v76, v71
	global_store_dwordx2 v[68:69], v[70:71], off
	v_mul_f32_e32 v71, 0xbfb8aa3b, v65
	v_exp_f32_e32 v71, v71
	s_nop 0
	v_add_f32_e32 v71, 1.0, v71
	v_rcp_f32_e32 v200, v72
	s_nop 0
	v_mul_f32_e32 v70, v64, v200
	v_mul_f32_e32 v72, 0xbfb8aa3b, v66
	v_exp_f32_e32 v72, v72
	s_nop 0
	v_add_f32_e32 v72, 1.0, v72
	v_div_scale_f32 v73, s[8:9], v72, v72, v66
	v_rcp_f32_e32 v74, v73
	v_mul_f32_e32 v69, 0xbfb8aa3b, v67
	v_rcp_f32_e32 v202, v71
	s_nop 0
	v_mul_f32_e32 v71, v65, v202
	v_fma_f32 v64, -v73, v74, 1.0
	v_exp_f32_e32 v69, v69
	v_fmac_f32_e32 v74, v64, v74
	v_add_f32_e32 v69, 1.0, v69
	v_div_scale_f32 v73, s[8:9], v69, v69, v67
	v_rcp_f32_e32 v75, v73
	v_rcp_f32_e32 v204, v72
	s_nop 0
	v_mul_f32_e32 v72, v66, v204
	v_or_b32_e32 v68, 60, v124
	v_fma_f32 v64, -v73, v75, 1.0
	v_fmac_f32_e32 v75, v64, v75
	v_rcp_f32_e32 v206, v69
	s_nop 0
	v_mul_f32_e32 v67, v67, v206
	v_ashrrev_i32_e32 v69, 31, v68
	v_lshlrev_b64 v[64:65], 12, v[68:69]
	v_lshl_add_u64 v[64:65], v[122:123], 0, v[64:65]
	v_cvt_pk_bf16_f32 v66, v70, v71
	v_cvt_pk_bf16_f32 v67, v72, v67
	global_store_dwordx2 v[64:65], v[66:67], off
	s_waitcnt lgkmcnt(0)
	ds_write2_b32 v130, v40, v44 offset1:16
	ds_write2_b32 v130, v41, v45 offset0:68 offset1:84
	ds_write2_b32 v130, v42, v46 offset0:136 offset1:152
	ds_write2_b32 v130, v43, v47 offset0:204 offset1:220
	ds_write2_b32 v130, v56, v60 offset0:32 offset1:48
	ds_write2_b32 v130, v57, v61 offset0:100 offset1:116
	ds_write2_b32 v130, v58, v62 offset0:168 offset1:184
	ds_write2_b32 v130, v59, v63 offset0:236 offset1:252
	ds_write2_b32 v127, v32, v36 offset0:64 offset1:80
	ds_write2_b32 v127, v33, v37 offset0:132 offset1:148
	ds_write2_b32 v127, v34, v38 offset0:200 offset1:216
	ds_write2_b32 v131, v35, v39 offset0:12 offset1:28
	ds_write2_b32 v127, v48, v52 offset0:96 offset1:112
	ds_write2_b32 v127, v49, v53 offset0:164 offset1:180
	ds_write2_b32 v127, v50, v54 offset0:232 offset1:248
	ds_write2_b32 v131, v51, v55 offset0:44 offset1:60
	s_waitcnt lgkmcnt(0)
	ds_read_b128 v[56:59], v126
	ds_read_b128 v[60:63], v126 offset:1088
	ds_read_b128 v[52:55], v126 offset:2176
	ds_read_b128 v[48:51], v126 offset:3264
	s_waitcnt lgkmcnt(0)
	v_mul_f32_e32 v32, 0xbfb8aa3b, v56
	v_exp_f32_e32 v32, v32
	v_mul_f32_e32 v69, 0xbfb8aa3b, v57
	v_exp_f32_e32 v69, v69
	v_add_f32_e32 v64, 1.0, v32
	ds_read_b128 v[44:47], v126 offset:4352
	ds_read_b128 v[40:43], v126 offset:5440
	ds_read_b128 v[36:39], v126 offset:6528
	ds_read_b128 v[32:35], v126 offset:7616
	v_add_f32_e32 v67, 1.0, v69
	v_mul_f32_e32 v66, 0xbfb8aa3b, v58
	v_exp_f32_e32 v66, v66
	v_rcp_f32_e32 v200, v64
	s_nop 0
	v_mul_f32_e32 v56, v56, v200
	v_add_f32_e32 v66, 1.0, v66
	v_div_scale_f32 v68, s[8:9], v66, v66, v58
	v_rcp_f32_e32 v69, v68
	v_rcp_f32_e32 v202, v67
	s_nop 0
	v_mul_f32_e32 v57, v57, v202
	v_mul_f32_e32 v67, 0xbfb8aa3b, v59
	v_fma_f32 v64, -v68, v69, 1.0
	v_exp_f32_e32 v67, v67
	v_fmac_f32_e32 v69, v64, v69
	v_add_f32_e32 v67, 1.0, v67
	v_div_scale_f32 v68, s[8:9], v67, v67, v59
	v_rcp_f32_e32 v70, v68
	v_rcp_f32_e32 v204, v66
	s_nop 0
	v_mul_f32_e32 v58, v58, v204
	v_cvt_pk_bf16_f32 v56, v56, v57
	v_fma_f32 v64, -v68, v70, 1.0
	v_fmac_f32_e32 v70, v64, v70
	v_div_scale_f32 v64, vcc, v59, v67, v59
	v_mul_f32_e32 v65, 0xbfb8aa3b, v60
	v_exp_f32_e32 v65, v65
	v_rcp_f32_e32 v206, v67
	s_nop 0
	v_mul_f32_e32 v59, v59, v206
	v_cvt_pk_bf16_f32 v57, v58, v59
	v_add_f32_e32 v64, 1.0, v65
	v_div_scale_f32 v65, s[8:9], v64, v64, v60
	s_mov_b32 s8, 0x80000
	v_add_co_u32_e32 v58, vcc, s8, v120
	s_nop 1
	v_addc_co_u32_e32 v59, vcc, 0, v121, vcc
	global_store_dwordx2 v[58:59], v[56:57], off
	v_mul_f32_e32 v58, 0xbfb8aa3b, v61
	v_exp_f32_e32 v58, v58
	s_nop 0
	v_add_f32_e32 v58, 1.0, v58
	v_rcp_f32_e32 v200, v64
	s_nop 0
	v_mul_f32_e32 v56, v60, v200
	v_mul_f32_e32 v64, 0xbfb8aa3b, v62
	v_exp_f32_e32 v64, v64
	s_nop 0
	v_add_f32_e32 v59, 1.0, v64
	v_div_scale_f32 v64, s[8:9], v59, v59, v62
	v_rcp_f32_e32 v66, v64
	v_rcp_f32_e32 v202, v58
	s_nop 0
	v_mul_f32_e32 v57, v61, v202
	v_mul_f32_e32 v61, 0xbfb8aa3b, v63
	v_fma_f32 v58, -v64, v66, 1.0
	v_exp_f32_e32 v61, v61
	v_fmac_f32_e32 v66, v58, v66
	v_add_f32_e32 v61, 1.0, v61
	v_div_scale_f32 v64, s[8:9], v61, v61, v63
	v_rcp_f32_e32 v65, v64
	v_rcp_f32_e32 v204, v59
; DI void st4(u16* p, float a, float b, float c, float d) { u32x2 w = {cvtpk(a, b), cvtpk(c, d)}; *(u32x2*)p = w; }
;   DI void operator()(int m, int n, f32x4 v) const { st4(dst + (size_t)m * ld + n, v[0], v[1], v[2], v[3]); }
;   DI void operator()(int m, int n, f32x4 v) const {
;     float o[4];
; #pragma unroll
;     for (int q = 0; q < 4; ++q) o[q] = v[q] / (1.f + __expf(-v[q]));
;     st4(dst + (size_t)m * ld + n, o[0], o[1], o[2], o[3]);
	s_nop 0
	v_mul_f32_e32 v58, v62, v204
	v_cvt_pk_bf16_f32 v56, v56, v57
	v_fma_f32 v59, -v64, v65, 1.0
	v_fmac_f32_e32 v65, v59, v65
	v_div_scale_f32 v59, vcc, v63, v61, v63
	v_mul_f32_e32 v60, 0xbfb8aa3b, v52
	v_exp_f32_e32 v60, v60
	v_rcp_f32_e32 v206, v61
	s_nop 0
	v_mul_f32_e32 v59, v63, v206
	v_cvt_pk_bf16_f32 v57, v58, v59
	v_add_f32_e32 v60, 1.0, v60
	v_div_scale_f32 v61, s[8:9], v60, v60, v52
	s_mov_b32 s8, 0x84000
	v_add_co_u32_e32 v58, vcc, s8, v120
	s_nop 1
	v_addc_co_u32_e32 v59, vcc, 0, v121, vcc
	global_store_dwordx2 v[58:59], v[56:57], off
	v_mul_f32_e32 v58, 0xbfb8aa3b, v53
	v_exp_f32_e32 v58, v58
	s_nop 0
	v_add_f32_e32 v58, 1.0, v58
	v_rcp_f32_e32 v200, v60
	s_nop 0
	v_mul_f32_e32 v52, v52, v200
	v_mul_f32_e32 v60, 0xbfb8aa3b, v54
	v_exp_f32_e32 v60, v60
	s_nop 0
	v_add_f32_e32 v59, 1.0, v60
	v_div_scale_f32 v60, s[8:9], v59, v59, v54
	v_rcp_f32_e32 v62, v60
	v_rcp_f32_e32 v202, v58
	s_nop 0
	v_mul_f32_e32 v53, v53, v202
	v_mul_f32_e32 v58, 0xbfb8aa3b, v55
	v_fma_f32 v56, -v60, v62, 1.0
	v_exp_f32_e32 v58, v58
	v_fmac_f32_e32 v62, v56, v62
	v_add_f32_e32 v58, 1.0, v58
	v_div_scale_f32 v60, s[8:9], v58, v58, v55
	v_rcp_f32_e32 v61, v60
	v_rcp_f32_e32 v204, v59
	s_nop 0
	v_mul_f32_e32 v54, v54, v204
	v_cvt_pk_bf16_f32 v52, v52, v53
	v_fma_f32 v56, -v60, v61, 1.0
	v_fmac_f32_e32 v61, v56, v61
	v_div_scale_f32 v56, vcc, v55, v58, v55
	v_mul_f32_e32 v57, v56, v61
	v_fma_f32 v59, -v60, v57, v56
	v_mul_f32_e32 v57, 0xbfb8aa3b, v48
	v_exp_f32_e32 v57, v57
	v_rcp_f32_e32 v206, v58
	s_nop 0
	v_mul_f32_e32 v55, v55, v206
	v_cvt_pk_bf16_f32 v53, v54, v55
	v_add_f32_e32 v56, 1.0, v57
	v_div_scale_f32 v57, s[8:9], v56, v56, v48
	s_mov_b32 s8, 0x88000
	v_add_co_u32_e32 v54, vcc, s8, v120
	s_nop 1
	v_addc_co_u32_e32 v55, vcc, 0, v121, vcc
	global_store_dwordx2 v[54:55], v[52:53], off
	v_mul_f32_e32 v54, 0xbfb8aa3b, v49
	v_exp_f32_e32 v54, v54
	s_nop 0
	v_add_f32_e32 v54, 1.0, v54
	v_rcp_f32_e32 v200, v56
	s_nop 0
	v_mul_f32_e32 v48, v48, v200
	v_mul_f32_e32 v56, 0xbfb8aa3b, v50
	v_exp_f32_e32 v56, v56
	s_nop 0
	v_add_f32_e32 v55, 1.0, v56
	v_div_scale_f32 v56, s[8:9], v55, v55, v50
	v_rcp_f32_e32 v58, v56
	v_rcp_f32_e32 v202, v54
	s_nop 0
	v_mul_f32_e32 v49, v49, v202
	v_mul_f32_e32 v54, 0xbfb8aa3b, v51
	v_fma_f32 v52, -v56, v58, 1.0
	v_exp_f32_e32 v54, v54
	v_fmac_f32_e32 v58, v52, v58
	v_add_f32_e32 v54, 1.0, v54
	v_div_scale_f32 v56, s[8:9], v54, v54, v51
	v_rcp_f32_e32 v57, v56
	v_rcp_f32_e32 v204, v55
	s_nop 0
	v_mul_f32_e32 v50, v50, v204
	v_cvt_pk_bf16_f32 v48, v48, v49
	v_fma_f32 v52, -v56, v57, 1.0
	v_fmac_f32_e32 v57, v52, v57
	v_div_scale_f32 v52, vcc, v51, v54, v51
	v_mul_f32_e32 v53, v52, v57
	v_fma_f32 v55, -v56, v53, v52
	s_waitcnt lgkmcnt(0)
	v_mul_f32_e32 v53, 0xbfb8aa3b, v44
	v_exp_f32_e32 v53, v53
	v_rcp_f32_e32 v206, v54
	s_nop 0
	v_mul_f32_e32 v51, v51, v206
	v_cvt_pk_bf16_f32 v49, v50, v51
	v_add_f32_e32 v52, 1.0, v53
	v_div_scale_f32 v53, s[8:9], v52, v52, v44
	s_mov_b32 s8, 0x8c000
	v_add_co_u32_e32 v50, vcc, s8, v120
	s_nop 1
	v_addc_co_u32_e32 v51, vcc, 0, v121, vcc
	global_store_dwordx2 v[50:51], v[48:49], off
	v_mul_f32_e32 v50, 0xbfb8aa3b, v45
	v_exp_f32_e32 v50, v50
	s_nop 0
	v_add_f32_e32 v50, 1.0, v50
	v_rcp_f32_e32 v200, v52
	s_nop 0
	v_mul_f32_e32 v44, v44, v200
	v_mul_f32_e32 v52, 0xbfb8aa3b, v46
	v_exp_f32_e32 v52, v52
	s_nop 0
	v_add_f32_e32 v51, 1.0, v52
	v_div_scale_f32 v52, s[8:9], v51, v51, v46
	v_rcp_f32_e32 v54, v52
	v_rcp_f32_e32 v202, v50
	s_nop 0
	v_mul_f32_e32 v45, v45, v202
	v_mul_f32_e32 v50, 0xbfb8aa3b, v47
	v_fma_f32 v48, -v52, v54, 1.0
	v_exp_f32_e32 v50, v50
	v_fmac_f32_e32 v54, v48, v54
	v_add_f32_e32 v50, 1.0, v50
	v_div_scale_f32 v52, s[8:9], v50, v50, v47
	v_rcp_f32_e32 v53, v52
	v_rcp_f32_e32 v204, v51
	s_nop 0
	v_mul_f32_e32 v46, v46, v204
	v_cvt_pk_bf16_f32 v44, v44, v45
	v_fma_f32 v48, -v52, v53, 1.0
	v_fmac_f32_e32 v53, v48, v53
	v_div_scale_f32 v48, vcc, v47, v50, v47
	v_mul_f32_e32 v49, v48, v53
	v_fma_f32 v51, -v52, v49, v48
	v_mul_f32_e32 v49, 0xbfb8aa3b, v40
	v_exp_f32_e32 v49, v49
	v_rcp_f32_e32 v206, v50
	s_nop 0
	v_mul_f32_e32 v47, v47, v206
	v_cvt_pk_bf16_f32 v45, v46, v47
	v_add_f32_e32 v48, 1.0, v49
	v_div_scale_f32 v49, s[8:9], v48, v48, v40
	s_mov_b32 s8, 0x90000
	v_add_co_u32_e32 v46, vcc, s8, v120
	s_nop 1
	v_addc_co_u32_e32 v47, vcc, 0, v121, vcc
	global_store_dwordx2 v[46:47], v[44:45], off
	v_mul_f32_e32 v46, 0xbfb8aa3b, v41
	v_exp_f32_e32 v46, v46
	s_nop 0
	v_add_f32_e32 v46, 1.0, v46
	v_rcp_f32_e32 v200, v48
	s_nop 0
	v_mul_f32_e32 v40, v40, v200
	v_mul_f32_e32 v48, 0xbfb8aa3b, v42
	v_exp_f32_e32 v48, v48
	s_nop 0
	v_add_f32_e32 v47, 1.0, v48
	v_div_scale_f32 v48, s[8:9], v47, v47, v42
	v_rcp_f32_e32 v50, v48
	v_rcp_f32_e32 v202, v46
	s_nop 0
	v_mul_f32_e32 v41, v41, v202
	v_mul_f32_e32 v46, 0xbfb8aa3b, v43
	v_fma_f32 v44, -v48, v50, 1.0
	v_exp_f32_e32 v46, v46
	v_fmac_f32_e32 v50, v44, v50
	v_add_f32_e32 v46, 1.0, v46
	v_div_scale_f32 v48, s[8:9], v46, v46, v43
	v_rcp_f32_e32 v49, v48
	v_rcp_f32_e32 v204, v47
	s_nop 0
	v_mul_f32_e32 v42, v42, v204
	v_cvt_pk_bf16_f32 v40, v40, v41
	v_fma_f32 v44, -v48, v49, 1.0
	v_fmac_f32_e32 v49, v44, v49
	v_div_scale_f32 v44, vcc, v43, v46, v43
	v_mul_f32_e32 v45, v44, v49
	v_fma_f32 v47, -v48, v45, v44
	v_mul_f32_e32 v45, 0xbfb8aa3b, v36
	v_exp_f32_e32 v45, v45
	v_rcp_f32_e32 v206, v46
	s_nop 0
	v_mul_f32_e32 v43, v43, v206
	v_cvt_pk_bf16_f32 v41, v42, v43
	v_add_f32_e32 v44, 1.0, v45
	v_div_scale_f32 v45, s[8:9], v44, v44, v36
	s_mov_b32 s8, 0x94000
	v_add_co_u32_e32 v42, vcc, s8, v120
	s_nop 1
	v_addc_co_u32_e32 v43, vcc, 0, v121, vcc
	global_store_dwordx2 v[42:43], v[40:41], off
	v_mul_f32_e32 v42, 0xbfb8aa3b, v37
; DI void st4(u16* p, float a, float b, float c, float d) { u32x2 w = {cvtpk(a, b), cvtpk(c, d)}; *(u32x2*)p = w; }
;   DI void operator()(int m, int n, f32x4 v) const { st4(dst + (size_t)m * ld + n, v[0], v[1], v[2], v[3]); }
;   DI void operator()(int m, int n, f32x4 v) const {
;     float o[4];
; #pragma unroll
;     for (int q = 0; q < 4; ++q) o[q] = v[q] / (1.f + __expf(-v[q]));
;     st4(dst + (size_t)m * ld + n, o[0], o[1], o[2], o[3]);
	v_exp_f32_e32 v42, v42
	s_nop 0
	v_add_f32_e32 v42, 1.0, v42
	v_rcp_f32_e32 v200, v44
	s_nop 0
	v_mul_f32_e32 v36, v36, v200
	v_mul_f32_e32 v44, 0xbfb8aa3b, v38
	v_exp_f32_e32 v44, v44
	s_nop 0
	v_add_f32_e32 v43, 1.0, v44
	v_div_scale_f32 v44, s[8:9], v43, v43, v38
	v_rcp_f32_e32 v46, v44
	v_rcp_f32_e32 v202, v42
	s_nop 0
	v_mul_f32_e32 v37, v37, v202
	v_mul_f32_e32 v42, 0xbfb8aa3b, v39
	v_fma_f32 v40, -v44, v46, 1.0
	v_exp_f32_e32 v42, v42
	v_fmac_f32_e32 v46, v40, v46
	v_add_f32_e32 v42, 1.0, v42
	v_div_scale_f32 v44, s[8:9], v42, v42, v39
	v_rcp_f32_e32 v45, v44
	v_rcp_f32_e32 v204, v43
	s_nop 0
	v_mul_f32_e32 v38, v38, v204
	v_cvt_pk_bf16_f32 v36, v36, v37
	v_fma_f32 v40, -v44, v45, 1.0
	v_fmac_f32_e32 v45, v40, v45
	v_div_scale_f32 v40, vcc, v39, v42, v39
	v_mul_f32_e32 v41, v40, v45
	v_fma_f32 v43, -v44, v41, v40
	v_mul_f32_e32 v41, 0xbfb8aa3b, v32
	v_exp_f32_e32 v41, v41
	v_rcp_f32_e32 v206, v42
	s_nop 0
	v_mul_f32_e32 v39, v39, v206
	v_cvt_pk_bf16_f32 v37, v38, v39
	v_add_f32_e32 v40, 1.0, v41
	v_div_scale_f32 v41, s[8:9], v40, v40, v32
	s_mov_b32 s8, 0x98000
	v_add_co_u32_e32 v38, vcc, s8, v120
	s_nop 1
	v_addc_co_u32_e32 v39, vcc, 0, v121, vcc
	global_store_dwordx2 v[38:39], v[36:37], off
	v_mul_f32_e32 v38, 0xbfb8aa3b, v33
	v_exp_f32_e32 v38, v38
	s_nop 0
	v_add_f32_e32 v38, 1.0, v38
	v_rcp_f32_e32 v200, v40
	s_nop 0
	v_mul_f32_e32 v32, v32, v200
	v_mul_f32_e32 v40, 0xbfb8aa3b, v34
	v_exp_f32_e32 v40, v40
	s_nop 0
	v_add_f32_e32 v39, 1.0, v40
	v_div_scale_f32 v40, s[8:9], v39, v39, v34
	v_rcp_f32_e32 v42, v40
	v_rcp_f32_e32 v202, v38
	s_nop 0
	v_mul_f32_e32 v33, v33, v202
	v_mul_f32_e32 v38, 0xbfb8aa3b, v35
	v_fma_f32 v36, -v40, v42, 1.0
	v_exp_f32_e32 v38, v38
	v_fmac_f32_e32 v42, v36, v42
	v_add_f32_e32 v38, 1.0, v38
	v_div_scale_f32 v40, s[8:9], v38, v38, v35
	v_rcp_f32_e32 v41, v40
	v_rcp_f32_e32 v204, v39
	s_nop 0
	v_mul_f32_e32 v34, v34, v204
	s_mov_b32 s8, 0x9c000
	v_fma_f32 v36, -v40, v41, 1.0
	v_fmac_f32_e32 v41, v36, v41
	v_div_scale_f32 v36, vcc, v35, v38, v35
	v_mul_f32_e32 v37, v36, v41
	v_fma_f32 v39, -v40, v37, v36
	v_rcp_f32_e32 v206, v38
	s_nop 0
	v_mul_f32_e32 v35, v35, v206
	v_cvt_pk_bf16_f32 v32, v32, v33
	v_cvt_pk_bf16_f32 v33, v34, v35
	v_add_co_u32_e32 v34, vcc, s8, v120
	s_nop 1
	v_addc_co_u32_e32 v35, vcc, 0, v121, vcc
	global_store_dwordx2 v[34:35], v[32:33], off
	s_waitcnt lgkmcnt(0)
	ds_write2_b32 v130, v8, v12 offset1:16
	ds_write2_b32 v130, v9, v13 offset0:68 offset1:84
	ds_write2_b32 v130, v10, v14 offset0:136 offset1:152
	ds_write2_b32 v130, v11, v15 offset0:204 offset1:220
	ds_write2_b32 v130, v24, v28 offset0:32 offset1:48
	ds_write2_b32 v130, v25, v29 offset0:100 offset1:116
	ds_write2_b32 v130, v26, v30 offset0:168 offset1:184
	ds_write2_b32 v130, v27, v31 offset0:236 offset1:252
	ds_write2_b32 v127, v0, v4 offset0:64 offset1:80
	ds_write2_b32 v127, v1, v5 offset0:132 offset1:148
	ds_write2_b32 v127, v2, v6 offset0:200 offset1:216
	ds_write2_b32 v131, v3, v7 offset0:12 offset1:28
	ds_write2_b32 v127, v16, v20 offset0:96 offset1:112
	ds_write2_b32 v127, v17, v21 offset0:164 offset1:180
	ds_write2_b32 v127, v18, v22 offset0:232 offset1:248
	ds_write2_b32 v131, v19, v23 offset0:44 offset1:60
	s_waitcnt lgkmcnt(0)
	ds_read_b128 v[24:27], v126
	ds_read_b128 v[28:31], v126 offset:1088
	ds_read_b128 v[20:23], v126 offset:2176
	ds_read_b128 v[16:19], v126 offset:3264
	s_waitcnt lgkmcnt(0)
	v_mul_f32_e32 v0, 0xbfb8aa3b, v24
	v_exp_f32_e32 v0, v0
	v_mul_f32_e32 v37, 0xbfb8aa3b, v25
	v_exp_f32_e32 v37, v37
	v_add_f32_e32 v32, 1.0, v0
	ds_read_b128 v[12:15], v126 offset:4352
	ds_read_b128 v[8:11], v126 offset:5440
	ds_read_b128 v[4:7], v126 offset:6528
	ds_read_b128 v[0:3], v126 offset:7616
	v_add_f32_e32 v35, 1.0, v37
	v_mul_f32_e32 v34, 0xbfb8aa3b, v26
	v_exp_f32_e32 v34, v34
	v_rcp_f32_e32 v200, v32
	s_nop 0
	v_mul_f32_e32 v24, v24, v200
	v_add_f32_e32 v34, 1.0, v34
	v_div_scale_f32 v36, s[8:9], v34, v34, v26
	v_rcp_f32_e32 v37, v36
	v_rcp_f32_e32 v202, v35
	s_nop 0
	v_mul_f32_e32 v25, v25, v202
	v_mul_f32_e32 v35, 0xbfb8aa3b, v27
	v_fma_f32 v32, -v36, v37, 1.0
	v_exp_f32_e32 v35, v35
	v_fmac_f32_e32 v37, v32, v37
	v_add_f32_e32 v35, 1.0, v35
	v_div_scale_f32 v36, s[8:9], v35, v35, v27
	v_rcp_f32_e32 v38, v36
	v_rcp_f32_e32 v204, v34
	s_nop 0
	v_mul_f32_e32 v26, v26, v204
	v_cvt_pk_bf16_f32 v24, v24, v25
	v_fma_f32 v32, -v36, v38, 1.0
	v_fmac_f32_e32 v38, v32, v38
	v_div_scale_f32 v32, vcc, v27, v35, v27
	v_mul_f32_e32 v33, 0xbfb8aa3b, v28
	v_exp_f32_e32 v33, v33
	v_rcp_f32_e32 v206, v35
	s_nop 0
	v_mul_f32_e32 v27, v27, v206
	v_cvt_pk_bf16_f32 v25, v26, v27
	v_add_f32_e32 v32, 1.0, v33
	v_div_scale_f32 v33, s[8:9], v32, v32, v28
	s_mov_b32 s8, 0xa0000
	v_add_co_u32_e32 v26, vcc, s8, v120
	s_nop 1
	v_addc_co_u32_e32 v27, vcc, 0, v121, vcc
	global_store_dwordx2 v[26:27], v[24:25], off
	v_mul_f32_e32 v26, 0xbfb8aa3b, v29
	v_exp_f32_e32 v26, v26
	s_nop 0
	v_add_f32_e32 v26, 1.0, v26
	v_rcp_f32_e32 v200, v32
	s_nop 0
	v_mul_f32_e32 v24, v28, v200
	v_mul_f32_e32 v32, 0xbfb8aa3b, v30
	v_exp_f32_e32 v32, v32
	s_nop 0
	v_add_f32_e32 v27, 1.0, v32
	v_div_scale_f32 v32, s[8:9], v27, v27, v30
	v_rcp_f32_e32 v34, v32
	v_rcp_f32_e32 v202, v26
	s_nop 0
	v_mul_f32_e32 v25, v29, v202
	v_mul_f32_e32 v29, 0xbfb8aa3b, v31
	v_fma_f32 v26, -v32, v34, 1.0
	v_exp_f32_e32 v29, v29
	v_fmac_f32_e32 v34, v26, v34
	v_add_f32_e32 v29, 1.0, v29
	v_div_scale_f32 v32, s[8:9], v29, v29, v31
	v_rcp_f32_e32 v33, v32
	v_rcp_f32_e32 v204, v27
	s_nop 0
	v_mul_f32_e32 v26, v30, v204
	v_cvt_pk_bf16_f32 v24, v24, v25
	v_fma_f32 v27, -v32, v33, 1.0
	v_fmac_f32_e32 v33, v27, v33
	v_div_scale_f32 v27, vcc, v31, v29, v31
; DI void st4(u16* p, float a, float b, float c, float d) { u32x2 w = {cvtpk(a, b), cvtpk(c, d)}; *(u32x2*)p = w; }
;   DI void operator()(int m, int n, f32x4 v) const { st4(dst + (size_t)m * ld + n, v[0], v[1], v[2], v[3]); }
;   DI void operator()(int m, int n, f32x4 v) const {
;     float o[4];
; #pragma unroll
;     for (int q = 0; q < 4; ++q) o[q] = v[q] / (1.f + __expf(-v[q]));
;     st4(dst + (size_t)m * ld + n, o[0], o[1], o[2], o[3]);
	v_mul_f32_e32 v28, 0xbfb8aa3b, v20
	v_exp_f32_e32 v28, v28
	v_rcp_f32_e32 v206, v29
	s_nop 0
	v_mul_f32_e32 v27, v31, v206
	v_cvt_pk_bf16_f32 v25, v26, v27
	v_add_f32_e32 v28, 1.0, v28
	v_div_scale_f32 v29, s[8:9], v28, v28, v20
	s_mov_b32 s8, 0xa4000
	v_add_co_u32_e32 v26, vcc, s8, v120
	s_nop 1
	v_addc_co_u32_e32 v27, vcc, 0, v121, vcc
	global_store_dwordx2 v[26:27], v[24:25], off
	v_mul_f32_e32 v26, 0xbfb8aa3b, v21
	v_exp_f32_e32 v26, v26
	s_nop 0
	v_add_f32_e32 v26, 1.0, v26
	v_rcp_f32_e32 v200, v28
	s_nop 0
	v_mul_f32_e32 v20, v20, v200
	v_mul_f32_e32 v28, 0xbfb8aa3b, v22
	v_exp_f32_e32 v28, v28
	s_nop 0
	v_add_f32_e32 v27, 1.0, v28
	v_div_scale_f32 v28, s[8:9], v27, v27, v22
	v_rcp_f32_e32 v30, v28
	v_rcp_f32_e32 v202, v26
	s_nop 0
	v_mul_f32_e32 v21, v21, v202
	v_mul_f32_e32 v26, 0xbfb8aa3b, v23
	v_fma_f32 v24, -v28, v30, 1.0
	v_exp_f32_e32 v26, v26
	v_fmac_f32_e32 v30, v24, v30
	v_add_f32_e32 v26, 1.0, v26
	v_div_scale_f32 v28, s[8:9], v26, v26, v23
	v_rcp_f32_e32 v29, v28
	v_rcp_f32_e32 v204, v27
	s_nop 0
	v_mul_f32_e32 v22, v22, v204
	v_cvt_pk_bf16_f32 v20, v20, v21
	v_fma_f32 v24, -v28, v29, 1.0
	v_fmac_f32_e32 v29, v24, v29
	v_div_scale_f32 v24, vcc, v23, v26, v23
	v_mul_f32_e32 v25, v24, v29
	v_fma_f32 v27, -v28, v25, v24
	v_mul_f32_e32 v25, 0xbfb8aa3b, v16
	v_exp_f32_e32 v25, v25
	v_rcp_f32_e32 v206, v26
	s_nop 0
	v_mul_f32_e32 v23, v23, v206
	v_cvt_pk_bf16_f32 v21, v22, v23
	v_add_f32_e32 v24, 1.0, v25
	v_div_scale_f32 v25, s[8:9], v24, v24, v16
	s_mov_b32 s8, 0xa8000
	v_add_co_u32_e32 v22, vcc, s8, v120
	s_nop 1
	v_addc_co_u32_e32 v23, vcc, 0, v121, vcc
	global_store_dwordx2 v[22:23], v[20:21], off
	v_mul_f32_e32 v22, 0xbfb8aa3b, v17
	v_exp_f32_e32 v22, v22
	s_nop 0
	v_add_f32_e32 v22, 1.0, v22
	v_rcp_f32_e32 v200, v24
	s_nop 0
	v_mul_f32_e32 v16, v16, v200
	v_mul_f32_e32 v24, 0xbfb8aa3b, v18
	v_exp_f32_e32 v24, v24
	s_nop 0
	v_add_f32_e32 v23, 1.0, v24
	v_div_scale_f32 v24, s[8:9], v23, v23, v18
	v_rcp_f32_e32 v26, v24
	v_rcp_f32_e32 v202, v22
	s_nop 0
	v_mul_f32_e32 v17, v17, v202
	v_mul_f32_e32 v22, 0xbfb8aa3b, v19
	v_fma_f32 v20, -v24, v26, 1.0
	v_exp_f32_e32 v22, v22
	v_fmac_f32_e32 v26, v20, v26
	v_add_f32_e32 v22, 1.0, v22
	v_div_scale_f32 v24, s[8:9], v22, v22, v19
	v_rcp_f32_e32 v25, v24
	v_rcp_f32_e32 v204, v23
	s_nop 0
	v_mul_f32_e32 v18, v18, v204
	v_cvt_pk_bf16_f32 v16, v16, v17
	v_fma_f32 v20, -v24, v25, 1.0
	v_fmac_f32_e32 v25, v20, v25
	v_div_scale_f32 v20, vcc, v19, v22, v19
	v_mul_f32_e32 v21, v20, v25
	v_fma_f32 v23, -v24, v21, v20
	s_waitcnt lgkmcnt(0)
; DI void st4(u16* p, float a, float b, float c, float d) { u32x2 w = {cvtpk(a, b), cvtpk(c, d)}; *(u32x2*)p = w; }
;   DI void operator()(int m, int n, f32x4 v) const { st4(dst + (size_t)m * ld + n, v[0], v[1], v[2], v[3]); }
;   DI void operator()(int m, int n, f32x4 v) const {
;     float o[4];
; #pragma unroll
;     for (int q = 0; q < 4; ++q) o[q] = v[q] / (1.f + __expf(-v[q]));
;     st4(dst + (size_t)m * ld + n, o[0], o[1], o[2], o[3]);
	v_mul_f32_e32 v21, 0xbfb8aa3b, v12
	v_exp_f32_e32 v21, v21
	v_rcp_f32_e32 v206, v22
	s_nop 0
	v_mul_f32_e32 v19, v19, v206
	v_cvt_pk_bf16_f32 v17, v18, v19
	v_add_f32_e32 v20, 1.0, v21
	v_div_scale_f32 v21, s[8:9], v20, v20, v12
	s_mov_b32 s8, 0xac000
	v_add_co_u32_e32 v18, vcc, s8, v120
	s_nop 1
	v_addc_co_u32_e32 v19, vcc, 0, v121, vcc
	global_store_dwordx2 v[18:19], v[16:17], off
	v_mul_f32_e32 v18, 0xbfb8aa3b, v13
	v_exp_f32_e32 v18, v18
	s_nop 0
	v_add_f32_e32 v18, 1.0, v18
	v_rcp_f32_e32 v200, v20
	s_nop 0
	v_mul_f32_e32 v12, v12, v200
	v_mul_f32_e32 v20, 0xbfb8aa3b, v14
	v_exp_f32_e32 v20, v20
	s_nop 0
	v_add_f32_e32 v19, 1.0, v20
	v_div_scale_f32 v20, s[8:9], v19, v19, v14
	v_rcp_f32_e32 v22, v20
	v_rcp_f32_e32 v202, v18
	s_nop 0
	v_mul_f32_e32 v13, v13, v202
	v_mul_f32_e32 v18, 0xbfb8aa3b, v15
	v_fma_f32 v16, -v20, v22, 1.0
	v_exp_f32_e32 v18, v18
	v_fmac_f32_e32 v22, v16, v22
	v_add_f32_e32 v18, 1.0, v18
	v_div_scale_f32 v20, s[8:9], v18, v18, v15
	v_rcp_f32_e32 v21, v20
	v_rcp_f32_e32 v204, v19
	s_nop 0
	v_mul_f32_e32 v14, v14, v204
	v_cvt_pk_bf16_f32 v12, v12, v13
	v_fma_f32 v16, -v20, v21, 1.0
	v_fmac_f32_e32 v21, v16, v21
	v_div_scale_f32 v16, vcc, v15, v18, v15
	v_mul_f32_e32 v17, v16, v21
	v_fma_f32 v19, -v20, v17, v16
	v_mul_f32_e32 v17, 0xbfb8aa3b, v8
	v_exp_f32_e32 v17, v17
	v_rcp_f32_e32 v206, v18
	s_nop 0
	v_mul_f32_e32 v15, v15, v206
	v_cvt_pk_bf16_f32 v13, v14, v15
	v_add_f32_e32 v16, 1.0, v17
	v_div_scale_f32 v17, s[8:9], v16, v16, v8
	s_mov_b32 s8, 0xb0000
	v_add_co_u32_e32 v14, vcc, s8, v120
	s_nop 1
	v_addc_co_u32_e32 v15, vcc, 0, v121, vcc
	global_store_dwordx2 v[14:15], v[12:13], off
	v_mul_f32_e32 v14, 0xbfb8aa3b, v9
	v_exp_f32_e32 v14, v14
	s_nop 0
	v_add_f32_e32 v14, 1.0, v14
	v_rcp_f32_e32 v200, v16
	s_nop 0
	v_mul_f32_e32 v8, v8, v200
	v_mul_f32_e32 v16, 0xbfb8aa3b, v10
	v_exp_f32_e32 v16, v16
	s_nop 0
	v_add_f32_e32 v15, 1.0, v16
	v_div_scale_f32 v16, s[8:9], v15, v15, v10
	v_rcp_f32_e32 v18, v16
	v_rcp_f32_e32 v202, v14
	s_nop 0
	v_mul_f32_e32 v9, v9, v202
	v_mul_f32_e32 v14, 0xbfb8aa3b, v11
	v_fma_f32 v12, -v16, v18, 1.0
	v_exp_f32_e32 v14, v14
	v_fmac_f32_e32 v18, v12, v18
	v_add_f32_e32 v14, 1.0, v14
	v_div_scale_f32 v16, s[8:9], v14, v14, v11
	v_rcp_f32_e32 v17, v16
	v_rcp_f32_e32 v204, v15
	s_nop 0
	v_mul_f32_e32 v10, v10, v204
	v_cvt_pk_bf16_f32 v8, v8, v9
	v_fma_f32 v12, -v16, v17, 1.0
	v_fmac_f32_e32 v17, v12, v17
	v_div_scale_f32 v12, vcc, v11, v14, v11
	v_mul_f32_e32 v13, v12, v17
	v_fma_f32 v15, -v16, v13, v12
	v_mul_f32_e32 v13, 0xbfb8aa3b, v4
	v_exp_f32_e32 v13, v13
	v_rcp_f32_e32 v206, v14
	s_nop 0
	v_mul_f32_e32 v11, v11, v206
	v_cvt_pk_bf16_f32 v9, v10, v11
	v_add_f32_e32 v12, 1.0, v13
	v_div_scale_f32 v13, s[8:9], v12, v12, v4
	s_mov_b32 s8, 0xb4000
	v_add_co_u32_e32 v10, vcc, s8, v120
	s_nop 1
	v_addc_co_u32_e32 v11, vcc, 0, v121, vcc
	global_store_dwordx2 v[10:11], v[8:9], off
	v_mul_f32_e32 v10, 0xbfb8aa3b, v5
	v_exp_f32_e32 v10, v10
	s_nop 0
	v_add_f32_e32 v10, 1.0, v10
	v_rcp_f32_e32 v200, v12
	s_nop 0
	v_mul_f32_e32 v4, v4, v200
	v_mul_f32_e32 v12, 0xbfb8aa3b, v6
	v_exp_f32_e32 v12, v12
	s_nop 0
	v_add_f32_e32 v11, 1.0, v12
	v_div_scale_f32 v12, s[8:9], v11, v11, v6
	v_rcp_f32_e32 v14, v12
	v_rcp_f32_e32 v202, v10
	s_nop 0
	v_mul_f32_e32 v5, v5, v202
	v_mul_f32_e32 v10, 0xbfb8aa3b, v7
	v_fma_f32 v8, -v12, v14, 1.0
	v_exp_f32_e32 v10, v10
	v_fmac_f32_e32 v14, v8, v14
	v_add_f32_e32 v10, 1.0, v10
	v_div_scale_f32 v12, s[8:9], v10, v10, v7
	v_rcp_f32_e32 v13, v12
	v_rcp_f32_e32 v204, v11
	s_nop 0
	v_mul_f32_e32 v6, v6, v204
	v_cvt_pk_bf16_f32 v4, v4, v5
	v_fma_f32 v8, -v12, v13, 1.0
	v_fmac_f32_e32 v13, v8, v13
	v_div_scale_f32 v8, vcc, v7, v10, v7
	v_mul_f32_e32 v9, v8, v13
	v_fma_f32 v11, -v12, v9, v8
	v_mul_f32_e32 v9, 0xbfb8aa3b, v0
	v_exp_f32_e32 v9, v9
	v_rcp_f32_e32 v206, v10
	s_nop 0
	v_mul_f32_e32 v7, v7, v206
	v_cvt_pk_bf16_f32 v5, v6, v7
	v_add_f32_e32 v8, 1.0, v9
	v_div_scale_f32 v9, s[8:9], v8, v8, v0
	s_mov_b32 s8, 0xb8000
	v_add_co_u32_e32 v6, vcc, s8, v120
	s_nop 1
	v_addc_co_u32_e32 v7, vcc, 0, v121, vcc
	global_store_dwordx2 v[6:7], v[4:5], off
	v_mul_f32_e32 v6, 0xbfb8aa3b, v1
	v_exp_f32_e32 v6, v6
	s_nop 0
	v_add_f32_e32 v6, 1.0, v6
	v_rcp_f32_e32 v200, v8
	s_nop 0
	v_mul_f32_e32 v0, v0, v200
	v_mul_f32_e32 v8, 0xbfb8aa3b, v2
	v_exp_f32_e32 v8, v8
	s_nop 0
	v_add_f32_e32 v7, 1.0, v8
	v_div_scale_f32 v8, s[8:9], v7, v7, v2
	v_rcp_f32_e32 v10, v8
	v_rcp_f32_e32 v202, v6
	s_nop 0
	v_mul_f32_e32 v1, v1, v202
	v_mul_f32_e32 v6, 0xbfb8aa3b, v3
	v_fma_f32 v4, -v8, v10, 1.0
	v_exp_f32_e32 v6, v6
	v_fmac_f32_e32 v10, v4, v10
	v_add_f32_e32 v6, 1.0, v6
	v_div_scale_f32 v8, s[8:9], v6, v6, v3
	v_rcp_f32_e32 v9, v8
	v_rcp_f32_e32 v204, v7
	s_nop 0
	v_mul_f32_e32 v2, v2, v204
	v_cvt_pk_bf16_f32 v0, v0, v1
	v_fma_f32 v4, -v8, v9, 1.0
	v_fmac_f32_e32 v9, v4, v9
	v_div_scale_f32 v4, vcc, v3, v6, v3
	v_mul_f32_e32 v5, v4, v9
	v_fma_f32 v7, -v8, v5, v4
	v_fmac_f32_e32 v5, v7, v9
	v_fma_f32 v4, -v8, v5, v4
	v_div_fmas_f32 v4, v4, v9, v5
	v_rcp_f32_e32 v206, v6
	s_nop 0
	v_mul_f32_e32 v3, v3, v206
	v_cvt_pk_bf16_f32 v1, v2, v3
	v_add_co_u32_e32 v2, vcc, 0xbc000, v120
	s_mov_b64 s[8:9], 0
	s_nop 0
	v_addc_co_u32_e32 v3, vcc, 0, v121, vcc
	global_store_dwordx2 v[2:3], v[0:1], off
	s_waitcnt lgkmcnt(0)
	s_andn2_b64 vcc, exec, s[74:75]
	s_cbranch_vccnz .LBB0_224
	s_waitcnt vmcnt(0)
	s_barrier
	s_mov_b64 s[76:77], -1
	s_branch .LBB0_224
